# grid barrier: non-leader blocks poll the top-level generation word directly instead of the per-XCD generation (one atomic hop less per barrier)
# speedup vs baseline: 1.0717x; 1.0024x over previous
.LBB0_85:
	s_or_b64 exec, exec, s[8:9]
	s_waitcnt vmcnt(0)
	v_readfirstlane_b32 s3, v3
	v_sub_u32_e32 v4, 0, v2
	s_nop 0
	v_add_u32_e32 v3, s3, v1
	v_cvt_f32_u32_e32 v1, v2
	v_rcp_iflag_f32_e32 v1, v1
	s_nop 0
	v_mul_f32_e32 v1, 0x4f7ffffe, v1
	v_cvt_u32_f32_e32 v1, v1
	v_mul_lo_u32 v4, v4, v1
	v_mul_hi_u32 v4, v1, v4
	v_add_u32_e32 v1, v1, v4
	v_mul_hi_u32 v1, v3, v1
	v_mul_lo_u32 v4, v1, v2
	v_sub_u32_e32 v4, v3, v4
	v_cmp_ge_u32_e32 vcc, v4, v2
	v_add_u32_e32 v5, 1, v1
	s_nop 0
	v_cndmask_b32_e32 v1, v1, v5, vcc
	v_sub_u32_e32 v5, v4, v2
	v_cndmask_b32_e32 v4, v4, v5, vcc
	v_cmp_ge_u32_e32 vcc, v4, v2
	v_add_u32_e32 v4, 1, v1
	s_nop 0
	v_cndmask_b32_e32 v1, v1, v4, vcc
	v_add_u32_e32 v4, 1, v3
	v_mad_u64_u32 v[2:3], s[6:7], v2, v1, v[2:3]
	v_cmp_ne_u32_e32 vcc, v4, v2
	s_and_saveexec_b64 s[6:7], vcc
	s_xor_b64 s[6:7], exec, s[6:7]
	s_cbranch_execz .LBB0_99
	v_mov_b32_e32 v0, 0x3100
	global_load_dword v0, v0, s[92:93] offset:1024 sc1
	s_add_u32 s12, s92, 0x3500
	s_addc_u32 s13, s93, 0
	s_waitcnt vmcnt(0)
	v_cmp_eq_u32_e32 vcc, v0, v1
	s_and_saveexec_b64 s[8:9], vcc
	s_cbranch_execz .LBB0_98
	s_mov_b32 s3, 1
	s_mov_b64 s[56:57], 0
	v_mov_b32_e32 v0, 0
	s_branch .LBB0_89

.LBB0_140:
	s_or_b64 exec, exec, s[12:13]
	s_waitcnt vmcnt(0)
	v_readfirstlane_b32 s0, v3
	v_sub_u32_e32 v4, 0, v2
	s_nop 0
	v_add_u32_e32 v3, s0, v1
	v_cvt_f32_u32_e32 v1, v2
	v_rcp_iflag_f32_e32 v1, v1
	s_nop 0
	v_mul_f32_e32 v1, 0x4f7ffffe, v1
	v_cvt_u32_f32_e32 v1, v1
	v_mul_lo_u32 v4, v4, v1
	v_mul_hi_u32 v4, v1, v4
	v_add_u32_e32 v1, v1, v4
	v_mul_hi_u32 v1, v3, v1
	v_mul_lo_u32 v4, v1, v2
	v_sub_u32_e32 v4, v3, v4
	v_cmp_ge_u32_e32 vcc, v4, v2
	v_add_u32_e32 v5, 1, v1
	s_nop 0
	v_cndmask_b32_e32 v1, v1, v5, vcc
	v_sub_u32_e32 v5, v4, v2
	v_cndmask_b32_e32 v4, v4, v5, vcc
	v_cmp_ge_u32_e32 vcc, v4, v2
	v_add_u32_e32 v4, 1, v1
	s_nop 0
	v_cndmask_b32_e32 v1, v1, v4, vcc
	v_add_u32_e32 v4, 1, v3
	v_mad_u64_u32 v[2:3], s[0:1], v2, v1, v[2:3]
	v_cmp_ne_u32_e32 vcc, v4, v2
	s_and_saveexec_b64 s[0:1], vcc
	s_xor_b64 s[8:9], exec, s[0:1]
	s_cbranch_execz .LBB0_154
	v_mov_b32_e32 v0, 0x3100
	global_load_dword v0, v0, s[92:93] offset:1024 sc1
	s_add_u32 s56, s92, 0x3500
	s_addc_u32 s57, s93, 0
	s_waitcnt vmcnt(0)
	v_cmp_eq_u32_e32 vcc, v0, v1
	s_and_saveexec_b64 s[12:13], vcc
	s_cbranch_execz .LBB0_153
	s_mov_b32 s0, 1
	s_mov_b64 s[60:61], 0
	v_mov_b32_e32 v0, 0
	s_branch .LBB0_144

.LBB0_241:
	s_or_b64 exec, exec, s[12:13]
	s_waitcnt vmcnt(0)
	v_readfirstlane_b32 s0, v3
	v_sub_u32_e32 v4, 0, v2
	s_nop 0
	v_add_u32_e32 v3, s0, v1
	v_cvt_f32_u32_e32 v1, v2
	v_rcp_iflag_f32_e32 v1, v1
	s_nop 0
	v_mul_f32_e32 v1, 0x4f7ffffe, v1
	v_cvt_u32_f32_e32 v1, v1
	v_mul_lo_u32 v4, v4, v1
	v_mul_hi_u32 v4, v1, v4
	v_add_u32_e32 v1, v1, v4
	v_mul_hi_u32 v1, v3, v1
	v_mul_lo_u32 v4, v1, v2
	v_sub_u32_e32 v4, v3, v4
	v_cmp_ge_u32_e32 vcc, v4, v2
	v_add_u32_e32 v5, 1, v1
	s_nop 0
	v_cndmask_b32_e32 v1, v1, v5, vcc
	v_sub_u32_e32 v5, v4, v2
	v_cndmask_b32_e32 v4, v4, v5, vcc
	v_cmp_ge_u32_e32 vcc, v4, v2
	v_add_u32_e32 v4, 1, v1
	s_nop 0
	v_cndmask_b32_e32 v1, v1, v4, vcc
	v_add_u32_e32 v4, 1, v3
	v_mad_u64_u32 v[2:3], s[0:1], v2, v1, v[2:3]
	v_cmp_ne_u32_e32 vcc, v4, v2
	s_and_saveexec_b64 s[0:1], vcc
	s_xor_b64 s[8:9], exec, s[0:1]
	s_cbranch_execz .LBB0_255
	v_mov_b32_e32 v0, 0x3100
	global_load_dword v0, v0, s[92:93] offset:1024 sc1
	s_add_u32 s48, s92, 0x3500
	s_addc_u32 s49, s93, 0
	s_waitcnt vmcnt(0)
	v_cmp_eq_u32_e32 vcc, v0, v1
	s_and_saveexec_b64 s[12:13], vcc
	s_cbranch_execz .LBB0_254
	s_mov_b32 s0, 1
	s_mov_b64 s[56:57], 0
	v_mov_b32_e32 v0, 0
	s_branch .LBB0_245

.LBB0_413:
	s_or_b64 exec, exec, s[10:11]
	s_waitcnt vmcnt(0)
	v_readfirstlane_b32 s0, v3
	v_sub_u32_e32 v4, 0, v2
	s_nop 0
	v_add_u32_e32 v3, s0, v1
	v_cvt_f32_u32_e32 v1, v2
	v_rcp_iflag_f32_e32 v1, v1
	s_nop 0
	v_mul_f32_e32 v1, 0x4f7ffffe, v1
	v_cvt_u32_f32_e32 v1, v1
	v_mul_lo_u32 v4, v4, v1
	v_mul_hi_u32 v4, v1, v4
	v_add_u32_e32 v1, v1, v4
	v_mul_hi_u32 v1, v3, v1
	v_mul_lo_u32 v4, v1, v2
	v_sub_u32_e32 v4, v3, v4
	v_cmp_ge_u32_e32 vcc, v4, v2
	v_add_u32_e32 v5, 1, v1
	s_nop 0
	v_cndmask_b32_e32 v1, v1, v5, vcc
	v_sub_u32_e32 v5, v4, v2
	v_cndmask_b32_e32 v4, v4, v5, vcc
	v_cmp_ge_u32_e32 vcc, v4, v2
	v_add_u32_e32 v4, 1, v1
	s_nop 0
	v_cndmask_b32_e32 v1, v1, v4, vcc
	v_add_u32_e32 v4, 1, v3
	v_mad_u64_u32 v[2:3], s[0:1], v2, v1, v[2:3]
	v_cmp_ne_u32_e32 vcc, v4, v2
	s_and_saveexec_b64 s[0:1], vcc
	s_xor_b64 s[8:9], exec, s[0:1]
	s_cbranch_execz .LBB0_427
	v_mov_b32_e32 v0, 0x3100
	global_load_dword v0, v0, s[92:93] offset:1024 sc1
	s_add_u32 s12, s92, 0x3500
	s_addc_u32 s13, s93, 0
	s_waitcnt vmcnt(0)
	v_cmp_eq_u32_e32 vcc, v0, v1
	s_and_saveexec_b64 s[10:11], vcc
	s_cbranch_execz .LBB0_426
	s_mov_b32 s0, 1
	s_mov_b64 s[48:49], 0
	v_mov_b32_e32 v0, 0
	s_branch .LBB0_417

.LBB0_601:
	s_or_b64 exec, exec, s[22:23]
	v_cvt_f32_u32_e32 v4, v2
	s_waitcnt vmcnt(0)
	v_readfirstlane_b32 s0, v3
	v_rcp_iflag_f32_e32 v4, v4
	s_nop 0
	v_add_u32_e32 v1, s0, v1
	v_add_u32_e32 v5, 1, v1
	v_mul_f32_e32 v3, 0x4f7ffffe, v4
	v_cvt_u32_f32_e32 v3, v3
	v_sub_u32_e32 v4, 0, v2
	v_mul_lo_u32 v4, v4, v3
	v_mul_hi_u32 v4, v3, v4
	v_add_u32_e32 v3, v3, v4
	v_mul_hi_u32 v3, v1, v3
	v_mul_lo_u32 v4, v3, v2
	v_sub_u32_e32 v1, v1, v4
	v_add_u32_e32 v6, 1, v3
	v_cmp_ge_u32_e32 vcc, v1, v2
	v_sub_u32_e32 v4, v1, v2
	s_nop 0
	v_cndmask_b32_e32 v3, v3, v6, vcc
	v_cndmask_b32_e32 v1, v1, v4, vcc
	v_add_u32_e32 v4, 1, v3
	v_cmp_ge_u32_e32 vcc, v1, v2
	s_nop 1
	v_cndmask_b32_e32 v1, v3, v4, vcc
	v_mad_u64_u32 v[2:3], s[0:1], v2, v1, v[2:3]
	v_cmp_ne_u32_e32 vcc, v5, v2
	s_and_saveexec_b64 s[0:1], vcc
	s_xor_b64 s[20:21], exec, s[0:1]
	s_cbranch_execz .LBB0_615
	v_mov_b32_e32 v0, 0x3100
	global_load_dword v0, v0, s[92:93] offset:1024 sc1
	s_add_u32 s48, s92, 0x3500
	s_addc_u32 s49, s93, 0
	s_waitcnt vmcnt(0)
	v_cmp_eq_u32_e32 vcc, v0, v1
	s_and_saveexec_b64 s[22:23], vcc
	s_cbranch_execz .LBB0_614
	s_mov_b32 s0, 1
	s_mov_b64 s[54:55], 0
	v_mov_b32_e32 v0, 0
	s_branch .LBB0_605

.LBB0_688:
	s_or_b64 exec, exec, s[20:21]
	v_cvt_f32_u32_e32 v4, v2
	s_waitcnt vmcnt(0)
	v_readfirstlane_b32 s0, v3
	v_rcp_iflag_f32_e32 v4, v4
	s_nop 0
	v_add_u32_e32 v1, s0, v1
	v_add_u32_e32 v5, 1, v1
	v_mul_f32_e32 v3, 0x4f7ffffe, v4
	v_cvt_u32_f32_e32 v3, v3
	v_sub_u32_e32 v4, 0, v2
	v_mul_lo_u32 v4, v4, v3
	v_mul_hi_u32 v4, v3, v4
	v_add_u32_e32 v3, v3, v4
	v_mul_hi_u32 v3, v1, v3
	v_mul_lo_u32 v4, v3, v2
	v_sub_u32_e32 v1, v1, v4
	v_add_u32_e32 v6, 1, v3
	v_cmp_ge_u32_e32 vcc, v1, v2
	v_sub_u32_e32 v4, v1, v2
	s_nop 0
	v_cndmask_b32_e32 v3, v3, v6, vcc
	v_cndmask_b32_e32 v1, v1, v4, vcc
	v_add_u32_e32 v4, 1, v3
	v_cmp_ge_u32_e32 vcc, v1, v2
	s_nop 1
	v_cndmask_b32_e32 v1, v3, v4, vcc
	v_mad_u64_u32 v[2:3], s[0:1], v2, v1, v[2:3]
	v_cmp_ne_u32_e32 vcc, v5, v2
	s_and_saveexec_b64 s[0:1], vcc
	s_xor_b64 s[16:17], exec, s[0:1]
	s_cbranch_execz .LBB0_702
	v_mov_b32_e32 v0, 0x3100
	global_load_dword v0, v0, s[92:93] offset:1024 sc1
	s_add_u32 s22, s92, 0x3500
	s_addc_u32 s23, s93, 0
	s_waitcnt vmcnt(0)
	v_cmp_eq_u32_e32 vcc, v0, v1
	s_and_saveexec_b64 s[20:21], vcc
	s_cbranch_execz .LBB0_701
	s_mov_b32 s0, 1
	s_mov_b64 s[24:25], 0
	v_mov_b32_e32 v0, 0
	s_branch .LBB0_692

.LBB0_788:
	s_or_b64 exec, exec, s[22:23]
	v_cvt_f32_u32_e32 v4, v2
	s_waitcnt vmcnt(0)
	v_readfirstlane_b32 s0, v3
	v_rcp_iflag_f32_e32 v4, v4
	s_nop 0
	v_add_u32_e32 v1, s0, v1
	v_add_u32_e32 v5, 1, v1
	v_mul_f32_e32 v3, 0x4f7ffffe, v4
	v_cvt_u32_f32_e32 v3, v3
	v_sub_u32_e32 v4, 0, v2
	v_mul_lo_u32 v4, v4, v3
	v_mul_hi_u32 v4, v3, v4
	v_add_u32_e32 v3, v3, v4
	v_mul_hi_u32 v3, v1, v3
	v_mul_lo_u32 v4, v3, v2
	v_sub_u32_e32 v1, v1, v4
	v_add_u32_e32 v6, 1, v3
	v_cmp_ge_u32_e32 vcc, v1, v2
	v_sub_u32_e32 v4, v1, v2
	s_nop 0
	v_cndmask_b32_e32 v3, v3, v6, vcc
	v_cndmask_b32_e32 v1, v1, v4, vcc
	v_add_u32_e32 v4, 1, v3
	v_cmp_ge_u32_e32 vcc, v1, v2
	s_nop 1
	v_cndmask_b32_e32 v1, v3, v4, vcc
	v_mad_u64_u32 v[2:3], s[0:1], v2, v1, v[2:3]
	v_cmp_ne_u32_e32 vcc, v5, v2
	s_and_saveexec_b64 s[0:1], vcc
	s_xor_b64 s[20:21], exec, s[0:1]
	s_cbranch_execz .LBB0_802
	v_mov_b32_e32 v0, 0x3100
	global_load_dword v0, v0, s[92:93] offset:1024 sc1
	s_add_u32 s24, s92, 0x3500
	s_addc_u32 s25, s93, 0
	s_waitcnt vmcnt(0)
	v_cmp_eq_u32_e32 vcc, v0, v1
	s_and_saveexec_b64 s[22:23], vcc
	s_cbranch_execz .LBB0_801
	s_mov_b32 s0, 1
	s_mov_b64 s[26:27], 0
	v_mov_b32_e32 v0, 0
	s_branch .LBB0_792

.LBB0_947:
	s_or_b64 exec, exec, s[10:11]
	v_cvt_f32_u32_e32 v4, v2
	s_waitcnt vmcnt(0)
	v_readfirstlane_b32 s0, v3
	v_rcp_iflag_f32_e32 v4, v4
	s_nop 0
	v_add_u32_e32 v1, s0, v1
	v_add_u32_e32 v5, 1, v1
	v_mul_f32_e32 v3, 0x4f7ffffe, v4
	v_cvt_u32_f32_e32 v3, v3
	v_sub_u32_e32 v4, 0, v2
	v_mul_lo_u32 v4, v4, v3
	v_mul_hi_u32 v4, v3, v4
	v_add_u32_e32 v3, v3, v4
	v_mul_hi_u32 v3, v1, v3
	v_mul_lo_u32 v4, v3, v2
	v_sub_u32_e32 v1, v1, v4
	v_add_u32_e32 v6, 1, v3
	v_cmp_ge_u32_e32 vcc, v1, v2
	v_sub_u32_e32 v4, v1, v2
	s_nop 0
	v_cndmask_b32_e32 v3, v3, v6, vcc
	v_cndmask_b32_e32 v1, v1, v4, vcc
	v_add_u32_e32 v4, 1, v3
	v_cmp_ge_u32_e32 vcc, v1, v2
	s_nop 1
	v_cndmask_b32_e32 v1, v3, v4, vcc
	v_mad_u64_u32 v[2:3], s[0:1], v2, v1, v[2:3]
	v_cmp_ne_u32_e32 vcc, v5, v2
	s_and_saveexec_b64 s[0:1], vcc
	s_xor_b64 s[8:9], exec, s[0:1]
	s_cbranch_execz .LBB0_961
	v_mov_b32_e32 v0, 0x3100
	global_load_dword v0, v0, s[92:93] offset:1024 sc1
	s_add_u32 s12, s92, 0x3500
	s_addc_u32 s13, s93, 0
	s_waitcnt vmcnt(0)
	v_cmp_eq_u32_e32 vcc, v0, v1
	s_and_saveexec_b64 s[10:11], vcc
	s_cbranch_execz .LBB0_960
	s_mov_b32 s0, 1
	s_mov_b64 s[16:17], 0
	v_mov_b32_e32 v0, 0
	s_branch .LBB0_951

.LBB0_1004:
	s_or_b64 exec, exec, s[10:11]
	v_cvt_f32_u32_e32 v4, v2
	s_waitcnt vmcnt(0)
	v_readfirstlane_b32 s0, v3
	v_rcp_iflag_f32_e32 v4, v4
	s_nop 0
	v_add_u32_e32 v1, s0, v1
	v_add_u32_e32 v5, 1, v1
	v_mul_f32_e32 v3, 0x4f7ffffe, v4
	v_cvt_u32_f32_e32 v3, v3
	v_sub_u32_e32 v4, 0, v2
	v_mul_lo_u32 v4, v4, v3
	v_mul_hi_u32 v4, v3, v4
	v_add_u32_e32 v3, v3, v4
	v_mul_hi_u32 v3, v1, v3
	v_mul_lo_u32 v4, v3, v2
	v_sub_u32_e32 v1, v1, v4
	v_add_u32_e32 v6, 1, v3
	v_cmp_ge_u32_e32 vcc, v1, v2
	v_sub_u32_e32 v4, v1, v2
	s_nop 0
	v_cndmask_b32_e32 v3, v3, v6, vcc
	v_cndmask_b32_e32 v1, v1, v4, vcc
	v_add_u32_e32 v4, 1, v3
	v_cmp_ge_u32_e32 vcc, v1, v2
	s_nop 1
	v_cndmask_b32_e32 v1, v3, v4, vcc
	v_mad_u64_u32 v[2:3], s[0:1], v2, v1, v[2:3]
	v_cmp_ne_u32_e32 vcc, v5, v2
	s_and_saveexec_b64 s[0:1], vcc
	s_xor_b64 s[8:9], exec, s[0:1]
	s_cbranch_execz .LBB0_1018
	v_mov_b32_e32 v0, 0x3100
	global_load_dword v0, v0, s[92:93] offset:1024 sc1
	s_add_u32 s12, s92, 0x3500
	s_addc_u32 s13, s93, 0
	s_waitcnt vmcnt(0)
	v_cmp_eq_u32_e32 vcc, v0, v1
	s_and_saveexec_b64 s[10:11], vcc
	s_cbranch_execz .LBB0_1017
	s_mov_b32 s0, 1
	s_mov_b64 s[14:15], 0
	v_mov_b32_e32 v0, 0
	s_branch .LBB0_1008
